# J2: grid barrier - wave 1 waits s_sleep 4 before the hoisted buffer_inv so the leader's arrival atomic is issued first; on top of N3
# speedup vs baseline: 1.0001x; 1.0001x over previous
.LBB0_577:
	s_waitcnt vmcnt(0)
	s_waitcnt vmcnt(0) lgkmcnt(0)
	s_barrier
	v_readlane_b32 s0, v255, 7
	s_nop 3
	s_cmp_lg_u32 s0, 1
	s_cbranch_scc1 .Lgb_noinv
	s_sleep 4
	buffer_inv sc1
